# gd_task loader: hand-written conv+silu+norm stage for interior tiles (v_fma_mix_f32 f16->f32 fused convert, fewer VALU ops)
# baseline (speedup 1.0000x reference)
; __device__ __forceinline__ float fsilu(float x) { return x * fsigmoid(x); }
; __device__ __forceinline__ h16x8 zeroh8() { h16x8 z; for (int i = 0; i < 8; ++i) z[i] = (h16)0.f; return z; }
; __device__ __forceinline__ void conv_silu8(const h16* pc, bool hp, bool hn, const float* cw, float* out) {
;     const h16x8 xc = ldh8(pc), xp = hp ? ldh8(pc - INC) : zeroh8(), xn = hn ? ldh8(pc + INC) : zeroh8();
;     const f32x4 w0a = *(const f32x4*)cw, w0b = *(const f32x4*)(cw + 4), w1a = *(const f32x4*)(cw + 3072), w1b = *(const f32x4*)(cw + 3076), w2a = *(const f32x4*)(cw + 6144), w2b = *(const f32x4*)(cw + 6148);
; #pragma unroll
;     for (int e = 0; e < 8; ++e) { const float a0 = e < 4 ? w0a[e & 3] : w0b[e & 3], a1 = e < 4 ? w1a[e & 3] : w1b[e & 3], a2 = e < 4 ? w2a[e & 3] : w2b[e & 3];
;         out[e] = fsilu((float)xp[e] * a0 + (float)xc[e] * a1 + (float)xn[e] * a2); }
; __device__ __forceinline__ void gd_task(const Params& p, LAS unsigned char* shm, const int tid, const int s, const int d, const int h, const int rq) {
;     ...
;                     const int js = ti * TT + st, t = d ? T - 1 - js : js; const size_t m = (size_t)base + t;
;                     const h16* pr = P + m * INC + GDC; const bool hp = t > 0, hn = t < T - 1;
;                     const h16 bbv = pr[4096 + h], aav = pr[4104 + d * 8 + h];
;                     float q[16], k[16];
;                     conv_silu8(pr + qcol, hp, hn, p.gd_conv + qcol, q); conv_silu8(pr + qcol + 8, hp, hn, p.gd_conv + qcol + 8, q + 8);
;                     conv_silu8(pr + kcol, hp, hn, p.gd_conv + kcol, k); conv_silu8(pr + kcol + 8, hp, hn, p.gd_conv + kcol + 8, k + 8);
;                     float v[4];
;                     { const h16* pc = pr + vcol; const h16x4 xc = *(const h16x4*)pc, xp = hp ? *(const h16x4*)(pc - INC) : (h16x4){(h16)0.f, (h16)0.f, (h16)0.f, (h16)0.f}, xn = hn ? *(const h16x4*)(pc + INC) : (h16x4){(h16)0.f, (h16)0.f, (h16)0.f, (h16)0.f};
;                       const f32x4 a0 = *(const f32x4*)(p.gd_conv + vcol), a1 = *(const f32x4*)(p.gd_conv + 3072 + vcol), a2 = *(const f32x4*)(p.gd_conv + 6144 + vcol);
.LBB0_333:
	s_cmp_eq_u32 s4, 0x1ff
	s_cbranch_scc1 .Lgdl_slow
	v_add_u32_e32 v2, 64, v204
	v_subrev_u32_e32 v3, 64, v193
	v_cndmask_b32_e64 v7, v3, v2, s[40:41]
	v_add_u32_e32 v4, 0x8000, v7
	v_mov_b64_e32 v[2:3], s[26:27]
	v_mad_i64_i32 v[2:3], s[0:1], v4, s89, v[2:3]
	s_mov_b64 s[0:1], 0x12e05a80
	s_nop 0
	v_lshl_add_u64 v[184:185], v[2:3], 0, s[0:1]
	v_lshl_add_u64 v[2:3], v[184:185], 0, s[16:17]
	v_add_co_u32_e32 v2, vcc, s88, v2
	v_lshl_add_u64 v[4:5], s[48:49], 1, v[184:185]
	s_nop 0
	v_addc_co_u32_e32 v3, vcc, 0, v3, vcc
	v_mov_b32_e32 v149, v0
	v_lshl_add_u64 v[218:219], v[184:185], 0, v[148:149]
	global_load_ushort v199, v[2:3], off
	global_load_ushort v149, v[4:5], off
	s_nop 0
	global_load_dwordx4 v[2:5], v[218:219], off
	v_add_co_u32_e32 v208, vcc, 0xffffc550, v218
	s_nop 1
	v_addc_co_u32_e32 v209, vcc, -1, v219, vcc
	v_add_co_u32_e32 v210, vcc, 0x3ab0, v218
	s_nop 1
	v_addc_co_u32_e32 v211, vcc, 0, v219, vcc
	global_load_dwordx4 v[10:13], v[208:209], off
	global_load_dwordx4 v[6:9], v[210:211], off
	global_load_dwordx4 v[14:17], v[150:151], off offset:16
	global_load_dwordx4 v[26:29], v[150:151], off
	global_load_dwordx4 v[22:25], v[152:153], off offset:16
	global_load_dwordx4 v[34:37], v[152:153], off
	global_load_dwordx4 v[18:21], v[154:155], off offset:16
	global_load_dwordx4 v[30:33], v[154:155], off
	global_load_dwordx4 v[42:45], v[218:219], off offset:16
	global_load_dwordx4 v[46:49], v[208:209], off offset:16
	global_load_dwordx4 v[38:41], v[210:211], off offset:16
	global_load_dwordx4 v[54:57], v[150:151], off offset:48
	global_load_dwordx4 v[66:69], v[150:151], off offset:32
	global_load_dwordx4 v[58:61], v[156:157], off offset:16
	global_load_dwordx4 v[70:73], v[156:157], off
	global_load_dwordx4 v[50:53], v[158:159], off offset:16
	global_load_dwordx4 v[62:65], v[158:159], off
	global_load_dwordx4 v[78:81], v[218:219], off offset:2048
	global_load_dwordx4 v[82:85], v[208:209], off offset:2048
	global_load_dwordx4 v[74:77], v[210:211], off offset:2048
	global_load_dwordx4 v[90:93], v[164:165], off offset:16
	global_load_dwordx4 v[102:105], v[164:165], off
	global_load_dwordx4 v[94:97], v[166:167], off offset:16
	global_load_dwordx4 v[106:109], v[166:167], off
	global_load_dwordx4 v[86:89], v[168:169], off offset:16
	global_load_dwordx4 v[98:101], v[168:169], off
	global_load_dwordx4 v[114:117], v[218:219], off offset:2064
	global_load_dwordx4 v[118:121], v[208:209], off offset:2064
	global_load_dwordx4 v[110:113], v[210:211], off offset:2064
	global_load_dwordx4 v[126:129], v[164:165], off offset:48
	global_load_dwordx4 v[138:141], v[164:165], off offset:32
	global_load_dwordx4 v[130:133], v[170:171], off offset:16
	global_load_dwordx4 v[142:145], v[170:171], off
	global_load_dwordx4 v[122:125], v[172:173], off offset:16
	global_load_dwordx4 v[134:137], v[172:173], off
	v_mov_b32_e32 v175, v0
	v_lshl_add_u64 v[190:191], v[184:185], 0, v[174:175]
	global_load_dwordx2 v[186:187], v[190:191], off
	v_add_co_u32_e32 v214, vcc, 0xffffc550, v190
	s_nop 1
	v_addc_co_u32_e32 v215, vcc, -1, v191, vcc
	v_add_co_u32_e32 v216, vcc, 0x3ab0, v190
	s_nop 1
	v_addc_co_u32_e32 v217, vcc, 0, v191, vcc
	global_load_dwordx2 v[188:189], v[214:215], off
	global_load_dwordx2 v[184:185], v[216:217], off
	global_load_dwordx4 v[220:223], v[176:177], off
	global_load_dwordx4 v[214:217], v[178:179], off
	global_load_dwordx4 v[208:211], v[180:181], off
	s_mov_b32 s6, 0xbfb8aa3b
	s_mov_b32 s0, 1.0
	s_waitcnt vmcnt(33)
	v_fma_mix_f32 v206, v2, v34, 0 op_sel:[0,0,0] op_sel_hi:[1,0,0]
	v_fma_mix_f32 v207, v2, v35, 0 op_sel:[1,0,0] op_sel_hi:[1,0,0]
	v_fma_mix_f32 v218, v3, v36, 0 op_sel:[0,0,0] op_sel_hi:[1,0,0]
	v_fma_mix_f32 v219, v3, v37, 0 op_sel:[1,0,0] op_sel_hi:[1,0,0]
	v_fma_mix_f32 v206, v10, v26, v206 op_sel:[0,0,0] op_sel_hi:[1,0,0]
	v_fma_mix_f32 v207, v10, v27, v207 op_sel:[1,0,0] op_sel_hi:[1,0,0]
	v_fma_mix_f32 v218, v11, v28, v218 op_sel:[0,0,0] op_sel_hi:[1,0,0]
	v_fma_mix_f32 v219, v11, v29, v219 op_sel:[1,0,0] op_sel_hi:[1,0,0]
	v_fma_mix_f32 v206, v6, v30, v206 op_sel:[0,0,0] op_sel_hi:[1,0,0]
	v_fma_mix_f32 v207, v6, v31, v207 op_sel:[1,0,0] op_sel_hi:[1,0,0]
	v_fma_mix_f32 v218, v7, v32, v218 op_sel:[0,0,0] op_sel_hi:[1,0,0]
	v_fma_mix_f32 v219, v7, v33, v219 op_sel:[1,0,0] op_sel_hi:[1,0,0]
	v_pk_mul_f32 v[240:241], v[206:207], s[6:7] op_sel_hi:[1,0]
	v_pk_mul_f32 v[190:191], v[218:219], s[6:7] op_sel_hi:[1,0]
	v_exp_f32_e32 v240, v240
	v_exp_f32_e32 v241, v241
	v_exp_f32_e32 v190, v190
	v_exp_f32_e32 v191, v191
	v_pk_add_f32 v[240:241], v[240:241], s[0:1] op_sel_hi:[1,0]
	v_pk_add_f32 v[190:191], v[190:191], s[0:1] op_sel_hi:[1,0]
	v_rcp_f32_e32 v240, v240
	v_rcp_f32_e32 v241, v241
	v_rcp_f32_e32 v190, v190
	v_rcp_f32_e32 v191, v191
	v_pk_mul_f32 v[34:35], v[206:207], v[240:241]
	v_pk_mul_f32 v[36:37], v[218:219], v[190:191]
	v_fma_mix_f32 v206, v4, v22, 0 op_sel:[0,0,0] op_sel_hi:[1,0,0]
	v_fma_mix_f32 v207, v4, v23, 0 op_sel:[1,0,0] op_sel_hi:[1,0,0]
	v_fma_mix_f32 v218, v5, v24, 0 op_sel:[0,0,0] op_sel_hi:[1,0,0]
	v_fma_mix_f32 v219, v5, v25, 0 op_sel:[1,0,0] op_sel_hi:[1,0,0]
	v_fma_mix_f32 v206, v12, v14, v206 op_sel:[0,0,0] op_sel_hi:[1,0,0]
	v_fma_mix_f32 v207, v12, v15, v207 op_sel:[1,0,0] op_sel_hi:[1,0,0]
	v_fma_mix_f32 v218, v13, v16, v218 op_sel:[0,0,0] op_sel_hi:[1,0,0]
	v_fma_mix_f32 v219, v13, v17, v219 op_sel:[1,0,0] op_sel_hi:[1,0,0]
	v_fma_mix_f32 v206, v8, v18, v206 op_sel:[0,0,0] op_sel_hi:[1,0,0]
	v_fma_mix_f32 v207, v8, v19, v207 op_sel:[1,0,0] op_sel_hi:[1,0,0]
	v_fma_mix_f32 v218, v9, v20, v218 op_sel:[0,0,0] op_sel_hi:[1,0,0]
	v_fma_mix_f32 v219, v9, v21, v219 op_sel:[1,0,0] op_sel_hi:[1,0,0]
	v_pk_mul_f32 v[240:241], v[206:207], s[6:7] op_sel_hi:[1,0]
	v_pk_mul_f32 v[190:191], v[218:219], s[6:7] op_sel_hi:[1,0]
	v_exp_f32_e32 v240, v240
	v_exp_f32_e32 v241, v241
	v_exp_f32_e32 v190, v190
	v_exp_f32_e32 v191, v191
	v_pk_add_f32 v[240:241], v[240:241], s[0:1] op_sel_hi:[1,0]
	v_pk_add_f32 v[190:191], v[190:191], s[0:1] op_sel_hi:[1,0]
	v_rcp_f32_e32 v240, v240
	v_rcp_f32_e32 v241, v241
	v_rcp_f32_e32 v190, v190
	v_rcp_f32_e32 v191, v191
	v_pk_mul_f32 v[22:23], v[206:207], v[240:241]
	v_pk_mul_f32 v[24:25], v[218:219], v[190:191]
	s_waitcnt vmcnt(24)
; __device__ __forceinline__ float fsilu(float x) { return x * fsigmoid(x); }
; __device__ __forceinline__ h16x8 zeroh8() { h16x8 z; for (int i = 0; i < 8; ++i) z[i] = (h16)0.f; return z; }
; __device__ __forceinline__ void conv_silu8(const h16* pc, bool hp, bool hn, const float* cw, float* out) {
;     const h16x8 xc = ldh8(pc), xp = hp ? ldh8(pc - INC) : zeroh8(), xn = hn ? ldh8(pc + INC) : zeroh8();
;     const f32x4 w0a = *(const f32x4*)cw, w0b = *(const f32x4*)(cw + 4), w1a = *(const f32x4*)(cw + 3072), w1b = *(const f32x4*)(cw + 3076), w2a = *(const f32x4*)(cw + 6144), w2b = *(const f32x4*)(cw + 6148);
; #pragma unroll
;     for (int e = 0; e < 8; ++e) { const float a0 = e < 4 ? w0a[e & 3] : w0b[e & 3], a1 = e < 4 ? w1a[e & 3] : w1b[e & 3], a2 = e < 4 ? w2a[e & 3] : w2b[e & 3];
;         out[e] = fsilu((float)xp[e] * a0 + (float)xc[e] * a1 + (float)xn[e] * a2); }
; __device__ __forceinline__ void gd_task(const Params& p, LAS unsigned char* shm, const int tid, const int s, const int d, const int h, const int rq) {
;     ...
;                     conv_silu8(pr + qcol, hp, hn, p.gd_conv + qcol, q); conv_silu8(pr + qcol + 8, hp, hn, p.gd_conv + qcol + 8, q + 8);
;                     conv_silu8(pr + kcol, hp, hn, p.gd_conv + kcol, k); conv_silu8(pr + kcol + 8, hp, hn, p.gd_conv + kcol + 8, k + 8);
	v_fma_mix_f32 v206, v42, v70, 0 op_sel:[0,0,0] op_sel_hi:[1,0,0]
	v_fma_mix_f32 v207, v42, v71, 0 op_sel:[1,0,0] op_sel_hi:[1,0,0]
	v_fma_mix_f32 v218, v43, v72, 0 op_sel:[0,0,0] op_sel_hi:[1,0,0]
	v_fma_mix_f32 v219, v43, v73, 0 op_sel:[1,0,0] op_sel_hi:[1,0,0]
	v_fma_mix_f32 v206, v46, v66, v206 op_sel:[0,0,0] op_sel_hi:[1,0,0]
	v_fma_mix_f32 v207, v46, v67, v207 op_sel:[1,0,0] op_sel_hi:[1,0,0]
	v_fma_mix_f32 v218, v47, v68, v218 op_sel:[0,0,0] op_sel_hi:[1,0,0]
	v_fma_mix_f32 v219, v47, v69, v219 op_sel:[1,0,0] op_sel_hi:[1,0,0]
	v_fma_mix_f32 v206, v38, v62, v206 op_sel:[0,0,0] op_sel_hi:[1,0,0]
	v_fma_mix_f32 v207, v38, v63, v207 op_sel:[1,0,0] op_sel_hi:[1,0,0]
	v_fma_mix_f32 v218, v39, v64, v218 op_sel:[0,0,0] op_sel_hi:[1,0,0]
	v_fma_mix_f32 v219, v39, v65, v219 op_sel:[1,0,0] op_sel_hi:[1,0,0]
	v_pk_mul_f32 v[240:241], v[206:207], s[6:7] op_sel_hi:[1,0]
	v_pk_mul_f32 v[190:191], v[218:219], s[6:7] op_sel_hi:[1,0]
	v_exp_f32_e32 v240, v240
	v_exp_f32_e32 v241, v241
	v_exp_f32_e32 v190, v190
	v_exp_f32_e32 v191, v191
	v_pk_add_f32 v[240:241], v[240:241], s[0:1] op_sel_hi:[1,0]
	v_pk_add_f32 v[190:191], v[190:191], s[0:1] op_sel_hi:[1,0]
	v_rcp_f32_e32 v240, v240
	v_rcp_f32_e32 v241, v241
	v_rcp_f32_e32 v190, v190
	v_rcp_f32_e32 v191, v191
	v_pk_mul_f32 v[70:71], v[206:207], v[240:241]
	v_pk_mul_f32 v[72:73], v[218:219], v[190:191]
	v_fma_mix_f32 v206, v44, v58, 0 op_sel:[0,0,0] op_sel_hi:[1,0,0]
	v_fma_mix_f32 v207, v44, v59, 0 op_sel:[1,0,0] op_sel_hi:[1,0,0]
	v_fma_mix_f32 v218, v45, v60, 0 op_sel:[0,0,0] op_sel_hi:[1,0,0]
	v_fma_mix_f32 v219, v45, v61, 0 op_sel:[1,0,0] op_sel_hi:[1,0,0]
	v_fma_mix_f32 v206, v48, v54, v206 op_sel:[0,0,0] op_sel_hi:[1,0,0]
	v_fma_mix_f32 v207, v48, v55, v207 op_sel:[1,0,0] op_sel_hi:[1,0,0]
	v_fma_mix_f32 v218, v49, v56, v218 op_sel:[0,0,0] op_sel_hi:[1,0,0]
	v_fma_mix_f32 v219, v49, v57, v219 op_sel:[1,0,0] op_sel_hi:[1,0,0]
	v_fma_mix_f32 v206, v40, v50, v206 op_sel:[0,0,0] op_sel_hi:[1,0,0]
	v_fma_mix_f32 v207, v40, v51, v207 op_sel:[1,0,0] op_sel_hi:[1,0,0]
	v_fma_mix_f32 v218, v41, v52, v218 op_sel:[0,0,0] op_sel_hi:[1,0,0]
	v_fma_mix_f32 v219, v41, v53, v219 op_sel:[1,0,0] op_sel_hi:[1,0,0]
	v_pk_mul_f32 v[240:241], v[206:207], s[6:7] op_sel_hi:[1,0]
	v_pk_mul_f32 v[190:191], v[218:219], s[6:7] op_sel_hi:[1,0]
	v_exp_f32_e32 v240, v240
	v_exp_f32_e32 v241, v241
	v_exp_f32_e32 v190, v190
	v_exp_f32_e32 v191, v191
	v_pk_add_f32 v[240:241], v[240:241], s[0:1] op_sel_hi:[1,0]
	v_pk_add_f32 v[190:191], v[190:191], s[0:1] op_sel_hi:[1,0]
	v_rcp_f32_e32 v240, v240
	v_rcp_f32_e32 v241, v241
	v_rcp_f32_e32 v190, v190
	v_rcp_f32_e32 v191, v191
	v_pk_mul_f32 v[58:59], v[206:207], v[240:241]
	v_pk_mul_f32 v[60:61], v[218:219], v[190:191]
	s_waitcnt vmcnt(15)
	v_fma_mix_f32 v206, v78, v106, 0 op_sel:[0,0,0] op_sel_hi:[1,0,0]
	v_fma_mix_f32 v207, v78, v107, 0 op_sel:[1,0,0] op_sel_hi:[1,0,0]
	v_fma_mix_f32 v218, v79, v108, 0 op_sel:[0,0,0] op_sel_hi:[1,0,0]
	v_fma_mix_f32 v219, v79, v109, 0 op_sel:[1,0,0] op_sel_hi:[1,0,0]
	v_fma_mix_f32 v206, v82, v102, v206 op_sel:[0,0,0] op_sel_hi:[1,0,0]
	v_fma_mix_f32 v207, v82, v103, v207 op_sel:[1,0,0] op_sel_hi:[1,0,0]
	v_fma_mix_f32 v218, v83, v104, v218 op_sel:[0,0,0] op_sel_hi:[1,0,0]
	v_fma_mix_f32 v219, v83, v105, v219 op_sel:[1,0,0] op_sel_hi:[1,0,0]
	v_fma_mix_f32 v206, v74, v98, v206 op_sel:[0,0,0] op_sel_hi:[1,0,0]
	v_fma_mix_f32 v207, v74, v99, v207 op_sel:[1,0,0] op_sel_hi:[1,0,0]
	v_fma_mix_f32 v218, v75, v100, v218 op_sel:[0,0,0] op_sel_hi:[1,0,0]
	v_fma_mix_f32 v219, v75, v101, v219 op_sel:[1,0,0] op_sel_hi:[1,0,0]
	v_pk_mul_f32 v[240:241], v[206:207], s[6:7] op_sel_hi:[1,0]
	v_pk_mul_f32 v[190:191], v[218:219], s[6:7] op_sel_hi:[1,0]
	v_exp_f32_e32 v240, v240
	v_exp_f32_e32 v241, v241
	v_exp_f32_e32 v190, v190
	v_exp_f32_e32 v191, v191
	v_pk_add_f32 v[240:241], v[240:241], s[0:1] op_sel_hi:[1,0]
	v_pk_add_f32 v[190:191], v[190:191], s[0:1] op_sel_hi:[1,0]
	v_rcp_f32_e32 v240, v240
	v_rcp_f32_e32 v241, v241
	v_rcp_f32_e32 v190, v190
	v_rcp_f32_e32 v191, v191
	v_pk_mul_f32 v[106:107], v[206:207], v[240:241]
	v_pk_mul_f32 v[108:109], v[218:219], v[190:191]
	v_fma_mix_f32 v206, v80, v94, 0 op_sel:[0,0,0] op_sel_hi:[1,0,0]
	v_fma_mix_f32 v207, v80, v95, 0 op_sel:[1,0,0] op_sel_hi:[1,0,0]
	v_fma_mix_f32 v218, v81, v96, 0 op_sel:[0,0,0] op_sel_hi:[1,0,0]
	v_fma_mix_f32 v219, v81, v97, 0 op_sel:[1,0,0] op_sel_hi:[1,0,0]
	v_fma_mix_f32 v206, v84, v90, v206 op_sel:[0,0,0] op_sel_hi:[1,0,0]
	v_fma_mix_f32 v207, v84, v91, v207 op_sel:[1,0,0] op_sel_hi:[1,0,0]
	v_fma_mix_f32 v218, v85, v92, v218 op_sel:[0,0,0] op_sel_hi:[1,0,0]
	v_fma_mix_f32 v219, v85, v93, v219 op_sel:[1,0,0] op_sel_hi:[1,0,0]
	v_fma_mix_f32 v206, v76, v86, v206 op_sel:[0,0,0] op_sel_hi:[1,0,0]
	v_fma_mix_f32 v207, v76, v87, v207 op_sel:[1,0,0] op_sel_hi:[1,0,0]
	v_fma_mix_f32 v218, v77, v88, v218 op_sel:[0,0,0] op_sel_hi:[1,0,0]
	v_fma_mix_f32 v219, v77, v89, v219 op_sel:[1,0,0] op_sel_hi:[1,0,0]
	v_pk_mul_f32 v[240:241], v[206:207], s[6:7] op_sel_hi:[1,0]
	v_pk_mul_f32 v[190:191], v[218:219], s[6:7] op_sel_hi:[1,0]
	v_exp_f32_e32 v240, v240
	v_exp_f32_e32 v241, v241
	v_exp_f32_e32 v190, v190
	v_exp_f32_e32 v191, v191
	v_pk_add_f32 v[240:241], v[240:241], s[0:1] op_sel_hi:[1,0]
	v_pk_add_f32 v[190:191], v[190:191], s[0:1] op_sel_hi:[1,0]
	v_rcp_f32_e32 v240, v240
	v_rcp_f32_e32 v241, v241
	v_rcp_f32_e32 v190, v190
	v_rcp_f32_e32 v191, v191
	v_pk_mul_f32 v[94:95], v[206:207], v[240:241]
	v_pk_mul_f32 v[96:97], v[218:219], v[190:191]
	s_waitcnt vmcnt(6)
; __device__ __forceinline__ float fsilu(float x) { return x * fsigmoid(x); }
; __device__ __forceinline__ h16x8 zeroh8() { h16x8 z; for (int i = 0; i < 8; ++i) z[i] = (h16)0.f; return z; }
; __device__ __forceinline__ void conv_silu8(const h16* pc, bool hp, bool hn, const float* cw, float* out) {
;     const h16x8 xc = ldh8(pc), xp = hp ? ldh8(pc - INC) : zeroh8(), xn = hn ? ldh8(pc + INC) : zeroh8();
;     const f32x4 w0a = *(const f32x4*)cw, w0b = *(const f32x4*)(cw + 4), w1a = *(const f32x4*)(cw + 3072), w1b = *(const f32x4*)(cw + 3076), w2a = *(const f32x4*)(cw + 6144), w2b = *(const f32x4*)(cw + 6148);
; #pragma unroll
;     for (int e = 0; e < 8; ++e) { const float a0 = e < 4 ? w0a[e & 3] : w0b[e & 3], a1 = e < 4 ? w1a[e & 3] : w1b[e & 3], a2 = e < 4 ? w2a[e & 3] : w2b[e & 3];
;         out[e] = fsilu((float)xp[e] * a0 + (float)xc[e] * a1 + (float)xn[e] * a2); }
; __device__ __forceinline__ void gd_task(const Params& p, LAS unsigned char* shm, const int tid, const int s, const int d, const int h, const int rq) {
;     ...
;                     conv_silu8(pr + qcol, hp, hn, p.gd_conv + qcol, q); conv_silu8(pr + qcol + 8, hp, hn, p.gd_conv + qcol + 8, q + 8);
;                     conv_silu8(pr + kcol, hp, hn, p.gd_conv + kcol, k); conv_silu8(pr + kcol + 8, hp, hn, p.gd_conv + kcol + 8, k + 8);
	v_fma_mix_f32 v206, v114, v142, 0 op_sel:[0,0,0] op_sel_hi:[1,0,0]
	v_fma_mix_f32 v207, v114, v143, 0 op_sel:[1,0,0] op_sel_hi:[1,0,0]
	v_fma_mix_f32 v218, v115, v144, 0 op_sel:[0,0,0] op_sel_hi:[1,0,0]
	v_fma_mix_f32 v219, v115, v145, 0 op_sel:[1,0,0] op_sel_hi:[1,0,0]
	v_fma_mix_f32 v206, v118, v138, v206 op_sel:[0,0,0] op_sel_hi:[1,0,0]
	v_fma_mix_f32 v207, v118, v139, v207 op_sel:[1,0,0] op_sel_hi:[1,0,0]
	v_fma_mix_f32 v218, v119, v140, v218 op_sel:[0,0,0] op_sel_hi:[1,0,0]
	v_fma_mix_f32 v219, v119, v141, v219 op_sel:[1,0,0] op_sel_hi:[1,0,0]
	v_fma_mix_f32 v206, v110, v134, v206 op_sel:[0,0,0] op_sel_hi:[1,0,0]
	v_fma_mix_f32 v207, v110, v135, v207 op_sel:[1,0,0] op_sel_hi:[1,0,0]
	v_fma_mix_f32 v218, v111, v136, v218 op_sel:[0,0,0] op_sel_hi:[1,0,0]
	v_fma_mix_f32 v219, v111, v137, v219 op_sel:[1,0,0] op_sel_hi:[1,0,0]
	v_pk_mul_f32 v[240:241], v[206:207], s[6:7] op_sel_hi:[1,0]
	v_pk_mul_f32 v[190:191], v[218:219], s[6:7] op_sel_hi:[1,0]
	v_exp_f32_e32 v240, v240
	v_exp_f32_e32 v241, v241
	v_exp_f32_e32 v190, v190
	v_exp_f32_e32 v191, v191
	v_pk_add_f32 v[240:241], v[240:241], s[0:1] op_sel_hi:[1,0]
	v_pk_add_f32 v[190:191], v[190:191], s[0:1] op_sel_hi:[1,0]
	v_rcp_f32_e32 v240, v240
	v_rcp_f32_e32 v241, v241
	v_rcp_f32_e32 v190, v190
	v_rcp_f32_e32 v191, v191
	v_pk_mul_f32 v[142:143], v[206:207], v[240:241]
	v_pk_mul_f32 v[144:145], v[218:219], v[190:191]
	v_fma_mix_f32 v206, v116, v130, 0 op_sel:[0,0,0] op_sel_hi:[1,0,0]
	v_fma_mix_f32 v207, v116, v131, 0 op_sel:[1,0,0] op_sel_hi:[1,0,0]
	v_fma_mix_f32 v218, v117, v132, 0 op_sel:[0,0,0] op_sel_hi:[1,0,0]
	v_fma_mix_f32 v219, v117, v133, 0 op_sel:[1,0,0] op_sel_hi:[1,0,0]
	v_fma_mix_f32 v206, v120, v126, v206 op_sel:[0,0,0] op_sel_hi:[1,0,0]
	v_fma_mix_f32 v207, v120, v127, v207 op_sel:[1,0,0] op_sel_hi:[1,0,0]
	v_fma_mix_f32 v218, v121, v128, v218 op_sel:[0,0,0] op_sel_hi:[1,0,0]
	v_fma_mix_f32 v219, v121, v129, v219 op_sel:[1,0,0] op_sel_hi:[1,0,0]
	v_fma_mix_f32 v206, v112, v122, v206 op_sel:[0,0,0] op_sel_hi:[1,0,0]
	v_fma_mix_f32 v207, v112, v123, v207 op_sel:[1,0,0] op_sel_hi:[1,0,0]
	v_fma_mix_f32 v218, v113, v124, v218 op_sel:[0,0,0] op_sel_hi:[1,0,0]
	v_fma_mix_f32 v219, v113, v125, v219 op_sel:[1,0,0] op_sel_hi:[1,0,0]
	v_pk_mul_f32 v[240:241], v[206:207], s[6:7] op_sel_hi:[1,0]
	v_pk_mul_f32 v[190:191], v[218:219], s[6:7] op_sel_hi:[1,0]
	v_exp_f32_e32 v240, v240
	v_exp_f32_e32 v241, v241
	v_exp_f32_e32 v190, v190
	v_exp_f32_e32 v191, v191
	v_pk_add_f32 v[240:241], v[240:241], s[0:1] op_sel_hi:[1,0]
	v_pk_add_f32 v[190:191], v[190:191], s[0:1] op_sel_hi:[1,0]
	v_rcp_f32_e32 v240, v240
	v_rcp_f32_e32 v241, v241
	v_rcp_f32_e32 v190, v190
	v_rcp_f32_e32 v191, v191
	v_pk_mul_f32 v[130:131], v[206:207], v[240:241]
	v_pk_mul_f32 v[132:133], v[218:219], v[190:191]
	s_waitcnt vmcnt(0)
; #define LAS __attribute__((address_space(3)))
; __device__ __forceinline__ float fsilu(float x) { return x * fsigmoid(x); }
; __device__ __forceinline__ void gd_task(const Params& p, LAS unsigned char* shm, const int tid, const int s, const int d, const int h, const int rq) {
;     ...
;                     { const h16* pc = pr + vcol; const h16x4 xc = *(const h16x4*)pc, xp = hp ? *(const h16x4*)(pc - INC) : (h16x4){(h16)0.f, (h16)0.f, (h16)0.f, (h16)0.f}, xn = hn ? *(const h16x4*)(pc + INC) : (h16x4){(h16)0.f, (h16)0.f, (h16)0.f, (h16)0.f};
;                       const f32x4 a0 = *(const f32x4*)(p.gd_conv + vcol), a1 = *(const f32x4*)(p.gd_conv + 3072 + vcol), a2 = *(const f32x4*)(p.gd_conv + 6144 + vcol);
; #pragma unroll
;                       for (int e = 0; e < 4; ++e) v[e] = fsilu((float)xp[e] * a0[e] + (float)xc[e] * a1[e] + (float)xn[e] * a2[e]); }
;                     float nq = 0.f, nk = 0.f;
; #pragma unroll
;                     for (int e = 0; e < 16; ++e) { nq += q[e] * q[e]; nk += k[e] * k[e]; }
;                     nq = red8(nq); nk = red8(nk);
;                     const float rq_ = rsqrtf(nq + 1e-6f) * 0.08838834764831845f, rk_ = rsqrtf(nk + 1e-6f);
;                     float kq = 0.f;
; #pragma unroll
;                     for (int e = 0; e < 16; ++e) { q[e] *= rq_; k[e] *= rk_; kq += q[e] * k[e]; }
;                     kq = red8(kq);
;                     LAS float* sb = inb + (ti & 1) * GD_INF + st * GD_STRIDE;
; #pragma unroll
;                     for (int e = 0; e < 4; ++e) { *(LAS f32x4*)(sb + 20 * jj + 4 * e) = (f32x4){k[4 * e], k[4 * e + 1], k[4 * e + 2], k[4 * e + 3]};
;                         *(LAS f32x4*)(sb + 160 + 20 * jj + 4 * e) = (f32x4){q[4 * e], q[4 * e + 1], q[4 * e + 2], q[4 * e + 3]}; }
;                     *(LAS f32x4*)(sb + 320 + 4 * jj) = (f32x4){v[0], v[1], v[2], v[3]};
	v_fma_mix_f32 v206, v186, v214, 0 op_sel:[0,0,0] op_sel_hi:[1,0,0]
	v_fma_mix_f32 v207, v186, v215, 0 op_sel:[1,0,0] op_sel_hi:[1,0,0]
	v_fma_mix_f32 v218, v187, v216, 0 op_sel:[0,0,0] op_sel_hi:[1,0,0]
	v_fma_mix_f32 v219, v187, v217, 0 op_sel:[1,0,0] op_sel_hi:[1,0,0]
	v_fma_mix_f32 v206, v188, v220, v206 op_sel:[0,0,0] op_sel_hi:[1,0,0]
	v_fma_mix_f32 v207, v188, v221, v207 op_sel:[1,0,0] op_sel_hi:[1,0,0]
	v_fma_mix_f32 v218, v189, v222, v218 op_sel:[0,0,0] op_sel_hi:[1,0,0]
	v_fma_mix_f32 v219, v189, v223, v219 op_sel:[1,0,0] op_sel_hi:[1,0,0]
	v_fma_mix_f32 v206, v184, v208, v206 op_sel:[0,0,0] op_sel_hi:[1,0,0]
	v_fma_mix_f32 v207, v184, v209, v207 op_sel:[1,0,0] op_sel_hi:[1,0,0]
	v_fma_mix_f32 v218, v185, v210, v218 op_sel:[0,0,0] op_sel_hi:[1,0,0]
	v_fma_mix_f32 v219, v185, v211, v219 op_sel:[1,0,0] op_sel_hi:[1,0,0]
	v_pk_mul_f32 v[240:241], v[206:207], s[6:7] op_sel_hi:[1,0]
	v_pk_mul_f32 v[190:191], v[218:219], s[6:7] op_sel_hi:[1,0]
	v_exp_f32_e32 v240, v240
	v_exp_f32_e32 v241, v241
	v_exp_f32_e32 v190, v190
	v_exp_f32_e32 v191, v191
	v_pk_add_f32 v[240:241], v[240:241], s[0:1] op_sel_hi:[1,0]
	v_pk_add_f32 v[190:191], v[190:191], s[0:1] op_sel_hi:[1,0]
	v_rcp_f32_e32 v240, v240
	v_rcp_f32_e32 v241, v241
	v_rcp_f32_e32 v190, v190
	v_rcp_f32_e32 v191, v191
	v_pk_mul_f32 v[214:215], v[206:207], v[240:241]
	v_pk_mul_f32 v[216:217], v[218:219], v[190:191]
	v_pk_mul_f32 v[206:207], v[34:35], v[34:35]
	v_pk_mul_f32 v[218:219], v[106:107], v[106:107]
	v_pk_fma_f32 v[206:207], v[36:37], v[36:37], v[206:207]
	v_pk_fma_f32 v[218:219], v[108:109], v[108:109], v[218:219]
	v_pk_fma_f32 v[206:207], v[22:23], v[22:23], v[206:207]
	v_pk_fma_f32 v[218:219], v[94:95], v[94:95], v[218:219]
	v_pk_fma_f32 v[206:207], v[24:25], v[24:25], v[206:207]
	v_pk_fma_f32 v[218:219], v[96:97], v[96:97], v[218:219]
	v_pk_fma_f32 v[206:207], v[70:71], v[70:71], v[206:207]
	v_pk_fma_f32 v[218:219], v[142:143], v[142:143], v[218:219]
	v_pk_fma_f32 v[206:207], v[72:73], v[72:73], v[206:207]
	v_pk_fma_f32 v[218:219], v[144:145], v[144:145], v[218:219]
	v_pk_fma_f32 v[206:207], v[58:59], v[58:59], v[206:207]
	v_pk_fma_f32 v[218:219], v[130:131], v[130:131], v[218:219]
	v_pk_fma_f32 v[206:207], v[60:61], v[60:61], v[206:207]
	v_pk_fma_f32 v[218:219], v[132:133], v[132:133], v[218:219]
	s_bitcmp1_b32 s4, 0
	v_add_f32_e32 v240, v206, v207
	v_add_f32_e32 v241, v218, v219
	s_cselect_b32 s0, 0xb200, 0
	v_add_f32_dpp v240, v240, v240 quad_perm:[1,0,3,2] row_mask:0xf bank_mask:0xf bound_ctrl:1
	v_add_f32_dpp v241, v241, v241 quad_perm:[1,0,3,2] row_mask:0xf bank_mask:0xf bound_ctrl:1
	v_add_u32_e32 v8, s0, v196
	v_add_f32_dpp v240, v240, v240 quad_perm:[2,3,0,1] row_mask:0xf bank_mask:0xf bound_ctrl:1
	v_add_f32_dpp v241, v241, v241 quad_perm:[2,3,0,1] row_mask:0xf bank_mask:0xf bound_ctrl:1
	v_lshl_add_u32 v212, v200, 2, v8
	v_add_f32_dpp v240, v240, v240 row_half_mirror row_mask:0xf bank_mask:0xf bound_ctrl:1
	v_add_f32_dpp v241, v241, v241 row_half_mirror row_mask:0xf bank_mask:0xf bound_ctrl:1
	v_add_u32_e32 v205, v212, v201
	s_nop 0
	v_add_f32_e32 v240, 0x358637bd, v240
	v_add_f32_e32 v241, 0x358637bd, v241
	v_rsq_f32_e32 v240, v240
	v_rsq_f32_e32 v241, v241
	s_nop 0
	v_mul_f32_e32 v240, 0x3db504f3, v240
	s_nop 0
	v_pk_mul_f32 v[2:3], v[34:35], v[240:241] op_sel_hi:[1,0]
	v_pk_mul_f32 v[18:19], v[106:107], v[240:241] op_sel:[0,1] op_sel_hi:[1,1]
	v_pk_mul_f32 v[4:5], v[36:37], v[240:241] op_sel_hi:[1,0]
	v_pk_mul_f32 v[20:21], v[108:109], v[240:241] op_sel:[0,1] op_sel_hi:[1,1]
	v_pk_mul_f32 v[42:43], v[22:23], v[240:241] op_sel_hi:[1,0]
	v_pk_mul_f32 v[26:27], v[94:95], v[240:241] op_sel:[0,1] op_sel_hi:[1,1]
	v_pk_mul_f32 v[44:45], v[24:25], v[240:241] op_sel_hi:[1,0]
	v_pk_mul_f32 v[28:29], v[96:97], v[240:241] op_sel:[0,1] op_sel_hi:[1,1]
	v_pk_mul_f32 v[46:47], v[70:71], v[240:241] op_sel_hi:[1,0]
	v_pk_mul_f32 v[30:31], v[142:143], v[240:241] op_sel:[0,1] op_sel_hi:[1,1]
	v_pk_mul_f32 v[48:49], v[72:73], v[240:241] op_sel_hi:[1,0]
	v_pk_mul_f32 v[32:33], v[144:145], v[240:241] op_sel:[0,1] op_sel_hi:[1,1]
	v_pk_mul_f32 v[14:15], v[58:59], v[240:241] op_sel_hi:[1,0]
	v_pk_mul_f32 v[38:39], v[130:131], v[240:241] op_sel:[0,1] op_sel_hi:[1,1]
	v_pk_mul_f32 v[16:17], v[60:61], v[240:241] op_sel_hi:[1,0]
	v_pk_mul_f32 v[40:41], v[132:133], v[240:241] op_sel:[0,1] op_sel_hi:[1,1]
	v_pk_mul_f32 v[190:191], v[2:3], v[18:19]
	v_pk_fma_f32 v[190:191], v[4:5], v[20:21], v[190:191]
	v_pk_fma_f32 v[190:191], v[42:43], v[26:27], v[190:191]
	v_pk_fma_f32 v[190:191], v[44:45], v[28:29], v[190:191]
	v_pk_fma_f32 v[190:191], v[46:47], v[30:31], v[190:191]
	v_pk_fma_f32 v[190:191], v[48:49], v[32:33], v[190:191]
	v_pk_fma_f32 v[190:191], v[14:15], v[38:39], v[190:191]
	v_pk_fma_f32 v[190:191], v[16:17], v[40:41], v[190:191]
	ds_write_b128 v212, v[18:21]
	v_add_f32_e32 v9, v190, v191
	ds_write_b128 v212, v[2:5] offset:640
	ds_write_b128 v212, v[26:29] offset:16
	v_add_f32_dpp v9, v9, v9 quad_perm:[1,0,3,2] row_mask:0xf bank_mask:0xf bound_ctrl:1
	ds_write_b128 v212, v[42:45] offset:656
	ds_write_b128 v212, v[30:33] offset:32
	v_add_f32_dpp v9, v9, v9 quad_perm:[2,3,0,1] row_mask:0xf bank_mask:0xf bound_ctrl:1
	ds_write_b128 v212, v[46:49] offset:672
	ds_write_b128 v212, v[38:41] offset:48
	v_add_f32_dpp v9, v9, v9 row_half_mirror row_mask:0xf bank_mask:0xf bound_ctrl:1
	ds_write_b128 v212, v[14:17] offset:688
	ds_write_b128 v205, v[214:217] offset:1280
	v_mov_b32_e32 v10, 0
	s_branch .Lgdl_sc

; #define LAS __attribute__((address_space(3)))
; __device__ __forceinline__ float softplusf_(float x) { return fmaxf(x, 0.f) + log1pf(expf(-fabsf(x))); }
; __device__ __forceinline__ float fsigmoid(float x) { return __builtin_amdgcn_rcpf(1.0f + __expf(-x)); }
; __device__ __forceinline__ void gd_task(const Params& p, LAS unsigned char* shm, const int tid, const int s, const int d, const int h, const int rq) {
;     ...
;                     if (jj == 0) { const float beta = fsigmoid((float)bbv); const float ain = (float)aav;
;                         const float g = alog * softplusf_(ain + dtb); const float wdec = __expf(g);
;                         *(LAS f32x4*)(sb + 352) = (f32x4){wdec, wdec * beta, kq, beta}; }
.Lgdl_sc:
	s_and_saveexec_b64 s[0:1], s[42:43]
	s_cbranch_execz .LBB0_332
	v_cvt_f32_f16_e32 v2, v199
	s_mov_b32 s6, 0xbfb8aa3b
	v_add_f32_e32 v4, v9, v10
	v_mul_f32_e32 v2, 0xbfb8aa3b, v2
	v_exp_f32_e32 v2, v2
	s_nop 0
	v_add_f32_e32 v2, 1.0, v2
	v_rcp_f32_e32 v5, v2
	v_cvt_f32_f16_e32 v2, v149
	v_add_f32_e32 v2, v192, v2
	v_mul_f32_e64 v3, |v2|, s6
	v_fma_f32 v6, |v2|, s6, -v3
	s_mov_b32 s6, 0xb2a5705f
	v_rndne_f32_e32 v7, v3
	v_fma_f32 v6, |v2|, s6, v6
	v_sub_f32_e32 v3, v3, v7
	v_add_f32_e32 v3, v3, v6
	v_exp_f32_e32 v3, v3
	v_cvt_i32_f32_e32 v6, v7
	s_mov_b32 s6, 0x42ce8ed0
	v_cmp_ngt_f32_e64 vcc, |v2|, s6
	s_mov_b32 s6, 0xc2b17218
	v_ldexp_f32 v3, v3, v6
	v_cndmask_b32_e32 v3, 0, v3, vcc
	v_cmp_nlt_f32_e64 vcc, |v2|, s6
	v_max_f32_e32 v9, 0, v2
	s_mov_b32 s6, 0x3f2aaaab
	v_cndmask_b32_e32 v20, v233, v3, vcc
	v_add_f32_e32 v6, 1.0, v20
	v_add_f32_e32 v2, -1.0, v6
	v_sub_f32_e32 v3, v2, v6
	v_add_f32_e32 v3, 1.0, v3
	v_sub_f32_e32 v2, v20, v2
	v_add_f32_e32 v7, v2, v3
	v_frexp_mant_f32_e32 v2, v6
	v_cmp_gt_f32_e32 vcc, s6, v2
	v_cvt_f64_f32_e32 v[2:3], v6
	v_frexp_exp_i32_f64_e32 v2, v[2:3]
	v_subbrev_co_u32_e32 v14, vcc, 0, v2, vcc
	v_sub_u32_e32 v2, 0, v14
	v_ldexp_f32 v3, v6, v2
	v_add_f32_e32 v6, -1.0, v3
	v_add_f32_e32 v10, 1.0, v3
	v_ldexp_f32 v2, v7, v2
	v_add_f32_e32 v7, 1.0, v6
	v_add_f32_e32 v11, -1.0, v10
	v_sub_f32_e32 v7, v3, v7
	v_sub_f32_e32 v3, v3, v11
	v_add_f32_e32 v7, v2, v7
	v_add_f32_e32 v2, v2, v3
	v_add_f32_e32 v15, v10, v2
	v_rcp_f32_e32 v17, v15
	v_sub_f32_e32 v3, v10, v15
	v_add_f32_e32 v16, v2, v3
	v_add_f32_e32 v3, v6, v7
	v_mul_f32_e32 v19, v3, v17
	v_sub_f32_e32 v2, v6, v3
	v_mul_f32_e32 v6, v15, v19
	v_fma_f32 v10, v19, v15, -v6
	v_fmac_f32_e32 v10, v19, v16
	v_add_f32_e32 v18, v7, v2
	v_add_f32_e32 v2, v6, v10
	v_sub_f32_e32 v7, v3, v2
	v_pk_add_f32 v[12:13], v[2:3], v[6:7] neg_lo:[0,1] neg_hi:[0,1]
	v_mov_b32_e32 v11, v2
	v_pk_add_f32 v[2:3], v[12:13], v[10:11] neg_lo:[0,1] neg_hi:[0,1]
	s_mov_b32 s6, 0x3f317218
	v_add_f32_e32 v3, v18, v3
	v_add_f32_e32 v2, v2, v3
	v_add_f32_e32 v3, v7, v2
	v_mul_f32_e32 v18, v17, v3
	v_mul_f32_e32 v6, v15, v18
	v_fma_f32 v10, v18, v15, -v6
	v_fmac_f32_e32 v10, v18, v16
	v_sub_f32_e32 v7, v7, v3
	v_add_f32_e32 v15, v2, v7
	v_add_f32_e32 v2, v6, v10
	v_sub_f32_e32 v7, v3, v2
	v_pk_add_f32 v[12:13], v[2:3], v[6:7] neg_lo:[0,1] neg_hi:[0,1]
	v_mov_b32_e32 v11, v2
	v_pk_add_f32 v[2:3], v[12:13], v[10:11] neg_lo:[0,1] neg_hi:[0,1]
	s_nop 0
	v_add_f32_e32 v3, v15, v3
	v_add_f32_e32 v2, v2, v3
	v_add_f32_e32 v3, v19, v18
	v_add_f32_e32 v2, v7, v2
	v_sub_f32_e32 v6, v3, v19
	v_mul_f32_e32 v2, v17, v2
	v_sub_f32_e32 v6, v18, v6
	v_add_f32_e32 v6, v6, v2
	v_add_f32_e32 v10, v3, v6
	v_mul_f32_e32 v11, v10, v10
	v_fmamk_f32 v2, v11, 0x3e9b6dac, v229
	v_fmaak_f32 v199, v11, v2, 0x3f2aaada
	v_cvt_f32_i32_e32 v2, v14
	v_sub_f32_e32 v3, v10, v3
	v_sub_f32_e32 v3, v6, v3
	v_ldexp_f32 v12, v3, 1
	v_mul_f32_e32 v3, v10, v11
	v_ldexp_f32 v7, v10, 1
	v_pk_mul_f32 v[10:11], v[2:3], v[198:199]
	s_nop 0
	v_fma_f32 v6, v2, s6, -v10
	v_fmac_f32_e32 v6, 0xb102e308, v2
	v_pk_add_f32 v[2:3], v[10:11], v[6:7]
	s_mov_b32 s6, 0x7f800000
	v_sub_f32_e32 v7, v3, v7
	v_sub_f32_e32 v7, v11, v7
	v_add_f32_e32 v13, v12, v7
	v_mov_b32_e32 v12, v10
	v_pk_add_f32 v[10:11], v[2:3], v[10:11] neg_lo:[0,1] neg_hi:[0,1]
	v_pk_add_f32 v[14:15], v[2:3], v[12:13]
	v_mov_b32_e32 v7, v2
	v_mov_b32_e32 v11, v15
	v_pk_add_f32 v[16:17], v[6:7], v[10:11] neg_lo:[0,1] neg_hi:[0,1]
	v_pk_add_f32 v[6:7], v[6:7], v[10:11]
	v_mov_b32_e32 v12, v13
	v_pk_add_f32 v[10:11], v[6:7], v[2:3] op_sel:[1,0] op_sel_hi:[0,1] neg_lo:[0,1] neg_hi:[0,1]
	v_pk_add_f32 v[18:19], v[14:15], v[10:11] op_sel_hi:[1,0] neg_lo:[0,1] neg_hi:[0,1]
	v_mov_b32_e32 v14, v15
	v_mov_b32_e32 v15, v7
	v_pk_mov_b32 v[10:11], v[2:3], v[10:11] op_sel:[1,0]
	v_mov_b32_e32 v13, v2
	v_pk_add_f32 v[10:11], v[14:15], v[10:11] neg_lo:[0,1] neg_hi:[0,1]
	v_mov_b32_e32 v18, v16
	v_pk_add_f32 v[2:3], v[12:13], v[10:11] neg_lo:[0,1] neg_hi:[0,1]
	v_mov_b32_e32 v17, v7
	v_pk_add_f32 v[10:11], v[18:19], v[2:3]
	v_cmp_neq_f32_e32 vcc, s6, v20
	v_pk_add_f32 v[12:13], v[10:11], v[10:11] op_sel:[0,1] op_sel_hi:[1,0]
	s_mov_b32 s6, 0x33800000
	v_pk_add_f32 v[6:7], v[6:7], v[12:13] op_sel:[1,0] op_sel_hi:[0,1]
	v_mov_b32_e32 v11, v6
	v_pk_add_f32 v[14:15], v[10:11], v[16:17] neg_lo:[0,1] neg_hi:[0,1]
	v_mov_b32_e32 v3, v12
	v_sub_f32_e32 v7, v10, v14
	v_pk_add_f32 v[2:3], v[2:3], v[14:15] neg_lo:[0,1] neg_hi:[0,1]
	v_sub_f32_e32 v7, v16, v7
	v_add_f32_e32 v2, v2, v7
	v_add_f32_e32 v2, v2, v3
	v_add_f32_e32 v2, v6, v2
	v_cndmask_b32_e32 v2, v233, v2, vcc
	v_cmp_lt_f32_e64 vcc, |v20|, s6
	s_nop 1
	v_cndmask_b32_e32 v2, v2, v20, vcc
	v_add_f32_e32 v2, v9, v2
	v_mul_f32_e32 v2, v2, v194
	v_mul_f32_e32 v2, 0xbfb8aa3b, v2
	v_exp_f32_e32 v2, v2
	s_nop 0
	v_mul_f32_e32 v3, v5, v2
	ds_write_b128 v8, v[2:5] offset:1408
	s_branch .LBB0_332
